# attention: next K/V tile global loads issued before the iteration barrier (right after the LDS stores) instead of after it
# speedup vs baseline: 1.0189x; 1.0105x over previous
; #define AT_LOAD(t) do { _Pragma("unroll") for (int i = 0; i < 2; ++i) { const int p = tid + 512 * i; \
;             kr[i] = *(const u32x4*)(kbase + (size_t)((t) * 64 + (p >> 4)) * HP1 + (p & 15) * 8); \
;             vr[i] = *(const u32x4*)(vbase + (size_t)(p >> 3) * R + (t) * 64 + (p & 7) * 8); } } while (0)
; #define AT_STORE(bo) do { _Pragma("unroll") for (int i = 0; i < 2; ++i) { const int p = tid + 512 * i; const int part = p & 15; \
;             *(LAS u32x4*)(lds + (bo) + (part >> 3) * AT_K2 + (p >> 4) * AT_KS + (part & 7) * 16) = kr[i]; \
;             *(LAS u32x4*)(lds + (bo) + AT_V + (p >> 3) * AT_KS + (p & 7) * 16) = vr[i]; } } while (0)
; #define AT_NOP() asm volatile("s_nop 7\n\ts_nop 7" ::: "memory")
; #define AT_RD4(d0, d1, d2, d3, addr, o0, o1, o2, o3) do { DSR(d0, addr, o0); DSR(d1, addr, o1); DSR(d2, addr, o2); DSR(d3, addr, o3); } while (0)
; __device__ __forceinline__ void attn_phase(KA a, lds8* lds, int tid, int lane, int wave) {
;     ...
;         const int q0 = seqb + 128 * qb; const int myrow = q0 + 32 * qg + l31;
;         bf16x8 qf[4];
; #pragma unroll
;         for (int ks = 0; ks < 4; ++ks) qf[ks] = *(const bf16x8*)(H + (size_t)myrow * HP1 + 1024 + h * 128 + map * 64 + 16 * ks + 8 * hh);
;         f32x16 O[4], negm = zero16;
; #pragma unroll
;         for (int db = 0; db < 4; ++db) O[db] = zero16;
;         float lsA = 0.f, lsB = 0.f, lsC = 0.f, lsD = 0.f;
;         const int nt = S / 64;
;         u32x4 kr[2], vr[2];
;         const bf16_t* kbase = H + (size_t)seqb * HP1 + 2048 + h * 128; const bf16_t* vbase = VT + (size_t)(h * 128) * R + seqb;
;     ...
;         bf16x8 pf[2][2]; bf16x8 kf[4], vf[8];
;         const unsigned lds0 = (unsigned)(size_t)lds;
;         const unsigned kaddr0 = lds0 + map * AT_K2 + krow_off, vaddr0 = lds0 + AT_V + vrow_off;
;         __syncthreads();
;         AT_LOAD(0); AT_STORE(0);
;         __syncthreads();
;         int bcur = 0, bprev = 2 * AT_BUF;
;         for (int t = 0; t < nt; ++t) {
;             const int bnext = bcur == 2 * AT_BUF ? 0 : bcur + AT_BUF;
;             if (t + 1 < nt) AT_LOAD(t + 1);
;             if (map == 1 && t > 0) { AT_PVRD(vaddr0 + bprev); AT_PVMM(vaddr0 + bprev); AT_NOP(); }
;             AT_RD4(kf[0], kf[1], kf[2], kf[3], kaddr0 + bcur, 0, 32, 64, 96); AT_RD4(vf[0], vf[1], vf[2], vf[3], kaddr0 + bcur, 4608, 4640, 4672, 4704);
.LBB0_1303:
	s_lshl_b32 s8, s15, 7
	s_add_i32 s8, s18, s8
	s_lshl_b32 s52, s14, 7
	v_or_b32_e32 v180, s8, v245
	v_mov_b64_e32 v[0:1], s[16:17]
	s_ashr_i32 s53, s52, 31
	v_mad_u64_u32 v[0:1], s[8:9], v180, s33, v[0:1]
	s_lshl_b64 s[12:13], s[52:53], 1
	s_mul_i32 s61, s18, 0x1800
	s_mul_hi_u32 s37, s18, 0x1800
	s_add_u32 s8, s16, s61
	s_addc_u32 s9, s17, s37
	s_add_u32 s8, s8, s12
	v_lshl_add_u64 v[0:1], v[0:1], 0, s[12:13]
	s_addc_u32 s9, s9, s13
	s_mul_i32 s62, s14, 0xc00000
	v_lshl_add_u64 v[0:1], v[0:1], 0, s[26:27]
	s_mul_hi_i32 s63, s52, 0x18000
	s_add_u32 s14, s10, s62
	v_lshl_add_u64 v[0:1], v[178:179], 1, v[0:1]
	s_addc_u32 s15, s11, s63
	s_lshl_b64 s[54:55], s[18:19], 1
	v_mov_b32_e32 v205, v181
	global_load_dwordx4 v[128:131], v[0:1], off offset:2048
	global_load_dwordx4 v[132:135], v[0:1], off offset:2080
	global_load_dwordx4 v[136:139], v[0:1], off offset:2112
	global_load_dwordx4 v[140:143], v[0:1], off offset:2144
	s_add_u32 s14, s14, s54
	v_lshl_add_u64 v[0:1], s[8:9], 0, v[204:205]
	s_addc_u32 s15, s15, s55
	v_lshl_add_u64 v[0:1], v[0:1], 0, s[28:29]
	v_mov_b32_e32 v207, v181
	v_lshl_add_u64 v[2:3], s[14:15], 0, v[206:207]
	v_lshl_add_u64 v[4:5], v[0:1], 0, v[184:185]
	v_lshl_add_u64 v[0:1], v[0:1], 0, v[188:189]
	s_barrier
	v_lshl_add_u64 v[6:7], v[2:3], 0, v[186:187]
	global_load_dwordx4 v[144:147], v[4:5], off
	global_load_dwordx4 v[148:151], v[6:7], off
	v_lshl_add_u64 v[2:3], v[2:3], 0, v[190:191]
	global_load_dwordx4 v[152:155], v[0:1], off
	global_load_dwordx4 v[156:159], v[2:3], off
	s_add_u32 s8, s12, s61
	s_addc_u32 s9, s13, s37
	v_mov_b32_e32 v14, v181
	v_mov_b32_e32 v15, v181
	v_lshl_add_u64 v[212:213], s[8:9], 0, v[196:197]
	v_lshl_add_u64 v[214:215], s[8:9], 0, v[198:199]
	s_add_u32 s8, s54, s62
	v_mov_b32_e32 v208, v181
	v_mov_b32_e32 v209, v181
	v_mov_b32_e32 v0, v181
	v_mov_b32_e32 v1, v181
	v_mov_b32_e32 v2, v181
	v_mov_b32_e32 v3, v181
	v_mov_b32_e32 v4, v181
	v_mov_b32_e32 v5, v181
	v_mov_b32_e32 v6, v181
	v_mov_b32_e32 v7, v181
	v_mov_b32_e32 v8, v181
	v_mov_b32_e32 v9, v181
	v_mov_b32_e32 v10, v181
	v_mov_b32_e32 v11, v181
	v_mov_b32_e32 v12, v181
	v_mov_b32_e32 v13, v181
	v_mov_b64_e32 v[30:31], v[14:15]
	v_mov_b64_e32 v[46:47], v[14:15]
	v_mov_b64_e32 v[62:63], v[14:15]
	v_mov_b64_e32 v[78:79], v[14:15]
	s_addc_u32 s9, s55, s63
	v_add_u32_e32 v96, v237, v238
	s_mov_b32 s14, 0x12000
	s_mov_b32 s15, 0
	s_mov_b32 s18, 0
	v_mov_b64_e32 v[28:29], v[12:13]
	v_mov_b64_e32 v[26:27], v[10:11]
	v_mov_b64_e32 v[24:25], v[8:9]
	v_mov_b64_e32 v[22:23], v[6:7]
	v_mov_b64_e32 v[20:21], v[4:5]
	v_mov_b64_e32 v[18:19], v[2:3]
	v_mov_b64_e32 v[16:17], v[0:1]
	v_mov_b64_e32 v[44:45], v[12:13]
	v_mov_b64_e32 v[42:43], v[10:11]
	v_mov_b64_e32 v[40:41], v[8:9]
	v_mov_b64_e32 v[38:39], v[6:7]
	v_mov_b64_e32 v[36:37], v[4:5]
	v_mov_b64_e32 v[34:35], v[2:3]
	v_mov_b64_e32 v[32:33], v[0:1]
	v_mov_b64_e32 v[60:61], v[12:13]
	v_mov_b64_e32 v[58:59], v[10:11]
	v_mov_b64_e32 v[56:57], v[8:9]
	v_mov_b64_e32 v[54:55], v[6:7]
	v_mov_b64_e32 v[52:53], v[4:5]
	v_mov_b64_e32 v[50:51], v[2:3]
	v_mov_b64_e32 v[48:49], v[0:1]
	v_mov_b64_e32 v[76:77], v[12:13]
	v_mov_b64_e32 v[74:75], v[10:11]
	v_mov_b64_e32 v[72:73], v[8:9]
	v_mov_b64_e32 v[70:71], v[6:7]
	v_mov_b64_e32 v[68:69], v[4:5]
	v_mov_b64_e32 v[66:67], v[2:3]
	v_mov_b64_e32 v[64:65], v[0:1]
	v_lshl_add_u64 v[216:217], s[8:9], 0, v[200:201]
	v_lshl_add_u64 v[218:219], s[8:9], 0, v[202:203]
	v_mov_b64_e32 v[210:211], v[208:209]
	v_add_u32_e32 v97, v236, v239
	v_add_u32_e32 v98, v237, v240
	v_add_u32_e32 v99, v236, v241
	s_waitcnt vmcnt(3)
	ds_write_b128 v96, v[144:147]
	s_waitcnt vmcnt(2)
	ds_write_b128 v97, v[148:151] offset:18432
	s_waitcnt vmcnt(1)
	ds_write_b128 v98, v[152:155]
	s_waitcnt vmcnt(0)
	ds_write_b128 v99, v[156:159] offset:18432
	v_lshl_add_u64 v[250:251], s[24:25], 0, v[214:215]
	v_lshl_add_u64 v[252:253], s[24:25], 0, v[218:219]
	global_load_dwordx4 v[144:147], v[250:251], off
	global_load_dwordx4 v[148:151], v[252:253], off
	v_lshl_add_u64 v[250:251], s[24:25], 0, v[212:213]
	v_lshl_add_u64 v[252:253], s[24:25], 0, v[216:217]
	global_load_dwordx4 v[152:155], v[250:251], off
	global_load_dwordx4 v[156:159], v[252:253], off
	s_waitcnt lgkmcnt(0)
	s_barrier
.LBB0_1304:
	s_add_i32 s61, s15, 1
	s_cmp_lt_u32 s61, s60
	s_cselect_b64 s[54:55], -1, 0
.LBB0_1306:
	s_cmp_eq_u32 s15, 0
	s_cselect_b64 s[8:9], -1, 0
	s_or_b64 s[8:9], s[30:31], s[8:9]
	s_and_b64 vcc, exec, s[8:9]
	s_cbranch_vccnz .LBB0_1308
	v_add_u32_e32 v168, s14, v232
	v_add_u32_e32 v249, s18, v244
	v_mfma_f32_32x32x16_bf16 v[48:63], v[96:99], v[88:91], v[48:63]
	v_mfma_f32_32x32x16_bf16 v[32:47], v[100:103], v[88:91], v[32:47]
	v_mfma_f32_32x32x16_bf16 v[16:31], v[104:107], v[88:91], v[16:31]
	v_mfma_f32_32x32x16_bf16 v[0:15], v[108:111], v[88:91], v[0:15]
	ds_read_b128 v[88:91], v168 offset:64
	ds_read_b128 v[96:99], v168 offset:0x1240
	ds_read_b128 v[100:103], v168 offset:0x2440
	ds_read_b128 v[104:107], v168 offset:0x3640
	ds_read_b128 v[108:111], v168 offset:0x60
	ds_read_b128 v[160:163], v168 offset:0x1260
	ds_read_b128 v[164:167], v168 offset:0x2460
	v_mfma_f32_32x32x16_bf16 v[48:63], v[112:115], v[92:95], v[48:63]
	v_mfma_f32_32x32x16_bf16 v[32:47], v[116:119], v[92:95], v[32:47]
	v_mfma_f32_32x32x16_bf16 v[16:31], v[120:123], v[92:95], v[16:31]
	v_mfma_f32_32x32x16_bf16 v[0:15], v[124:127], v[92:95], v[0:15]
	ds_read_b128 v[92:95], v168 offset:0x3660
	s_waitcnt lgkmcnt(0)
	ds_read_b128 v[112:115], v249 offset:0
	ds_read_b128 v[220:223], v249 offset:32
	ds_read_b128 v[224:227], v249 offset:64
	ds_read_b128 v[228:231], v249 offset:0x60
	ds_read_b128 v[116:119], v249 offset:0x1200
	ds_read_b128 v[120:123], v249 offset:0x1220
	ds_read_b128 v[168:171], v249 offset:0x1240
	ds_read_b128 v[172:175], v249 offset:0x1260
	v_mfma_f32_32x32x16_bf16 v[48:63], v[88:91], v[80:83], v[48:63]
	v_mfma_f32_32x32x16_bf16 v[32:47], v[96:99], v[80:83], v[32:47]
	v_mfma_f32_32x32x16_bf16 v[16:31], v[100:103], v[80:83], v[16:31]
	v_mfma_f32_32x32x16_bf16 v[0:15], v[104:107], v[80:83], v[0:15]
	v_mfma_f32_32x32x16_bf16 v[48:63], v[108:111], v[84:87], v[48:63]
	v_mfma_f32_32x32x16_bf16 v[32:47], v[160:163], v[84:87], v[32:47]
	v_mfma_f32_32x32x16_bf16 v[16:31], v[164:167], v[84:87], v[16:31]
	v_mfma_f32_32x32x16_bf16 v[0:15], v[92:95], v[84:87], v[0:15]
	s_branch .Lat_qk

; #define AT_LOAD(t) do { _Pragma("unroll") for (int i = 0; i < 2; ++i) { const int p = tid + 512 * i; \
;             kr[i] = *(const u32x4*)(kbase + (size_t)((t) * 64 + (p >> 4)) * HP1 + (p & 15) * 8); \
;             vr[i] = *(const u32x4*)(vbase + (size_t)(p >> 3) * R + (t) * 64 + (p & 7) * 8); } } while (0)
; #define AT_STORE(bo) do { _Pragma("unroll") for (int i = 0; i < 2; ++i) { const int p = tid + 512 * i; const int part = p & 15; \
;             *(LAS u32x4*)(lds + (bo) + (part >> 3) * AT_K2 + (p >> 4) * AT_KS + (part & 7) * 16) = kr[i]; \
;             *(LAS u32x4*)(lds + (bo) + AT_V + (p >> 3) * AT_KS + (p & 7) * 16) = vr[i]; } } while (0)
; __device__ __forceinline__ void attn_phase(KA a, lds8* lds, int tid, int lane, int wave) {
;     ...
;             if (t + 1 < nt) AT_LOAD(t + 1);
;     ...
;             if (t + 1 < nt) AT_STORE(bnext);
;             __syncthreads();
;             bprev = bcur; bcur = bnext;
.LBB0_1316:
	v_lshl_add_u64 v[212:213], v[212:213], 0, s[44:45]
	v_lshl_add_u64 v[214:215], v[214:215], 0, s[44:45]
	v_lshl_add_u64 v[216:217], v[216:217], 0, s[48:49]
	v_lshl_add_u64 v[218:219], v[218:219], 0, s[48:49]
	s_add_i32 s8, s61, 1
	s_cmp_ge_u32 s8, s60
	s_cbranch_scc1 .Lat_ld_skip
	v_lshl_add_u64 v[250:251], s[24:25], 0, v[214:215]
	v_lshl_add_u64 v[252:253], s[24:25], 0, v[218:219]
	global_load_dwordx4 v[144:147], v[250:251], off
	global_load_dwordx4 v[148:151], v[252:253], off
	v_lshl_add_u64 v[250:251], s[24:25], 0, v[212:213]
	v_lshl_add_u64 v[252:253], s[24:25], 0, v[216:217]
	global_load_dwordx4 v[152:155], v[250:251], off
	global_load_dwordx4 v[156:159], v[252:253], off
.Lat_ld_skip:
	s_cmp_eq_u32 s60, s61
	s_waitcnt lgkmcnt(0)
	s_barrier
	s_cbranch_scc1 .LBB0_1318
	s_mov_b32 s15, s61
	s_mov_b32 s14, s18
	s_mov_b32 s18, s62
	s_branch .LBB0_1304
